# k9
# speedup vs baseline: 1.0078x; 1.0008x over previous
; __device__ __forceinline__ unsigned cvtpk(float lo, float hi) { f32x2 v = {lo, hi}; bf16x2_t b = __builtin_convertvector(v, bf16x2_t); return __builtin_bit_cast(unsigned, b); }
; __device__ __forceinline__ void rs_prep(const float* ssq, int tok0, LAS float* rsl, int ui, int wv) {
;     ...
;     if (tid < 256) { const f32x4* s = (const f32x4*)(ssq + (size_t)(tok0 + tid) * 16); const f32x4 a = s[0], b = s[1], c = s[2], d = s[3];
;         const float t = ((a.x + a.y) + (a.z + a.w)) + ((b.x + b.y) + (b.z + b.w)) + ((c.x + c.y) + (c.z + c.w)) + ((d.x + d.y) + (d.z + d.w));
;     __device__ __forceinline__ void operator()(const f32x4 (&acc)[2][2][4][2], const Unit& u, int ui, int wr, int wc, int fr, int fq) const {
;     ...
;             for (int m = 0; m < 4; ++m) { const int rl = ai * HALF + wr * 64 + m * 16 + fr; const float rs = rsl[(ui & 1) * 256 + rl];
;                 float h[8];
; #pragma unroll
;                 for (int n = 0; n < 2; ++n)
; #pragma unroll
;                     for (int e = 0; e < 4; ++e) { const float g = acc[ai][0][m][n][e] * rs, up = acc[ai][1][m][n][e] * rs;
;                         h[n * 4 + e] = g * __builtin_amdgcn_rcpf(1.f + __builtin_amdgcn_exp2f(-g * LOG2E)) * up; }
;                 u32x4 w; w.x = cvtpk(h[0], h[1]); w.y = cvtpk(h[2], h[3]); w.z = cvtpk(h[4], h[5]); w.w = cvtpk(h[6], h[7]);
;                 *(u32x4*)(H + (size_t)(u.pm * 256 + rl) * DFF + col0) = w; }
.LBB0_1166:
	s_and_b64 vcc, exec, s[4:5]
	s_cbranch_vccz .Lffnup_pf_skip
	v_mbcnt_lo_u32_b32 v150, -1, 0
	v_mbcnt_hi_u32_b32 v150, -1, v150
	v_add_u32_e32 v150, s16, v150
	v_cmp_gt_i32_e32 vcc, s88, v150
	s_and_saveexec_b64 s[100:101], vcc
	s_cbranch_execz .Lffnup_pf_done
	v_lshl_add_u32 v152, s22, 8, v150
	v_ashrrev_i32_e32 v153, 31, v152
	v_lshlrev_b64 v[152:153], 6, v[152:153]
	v_lshl_add_u64 v[152:153], s[6:7], 0, v[152:153]
	global_load_dwordx4 v[154:157], v[152:153], off offset:48
	global_load_dwordx4 v[158:161], v[152:153], off offset:32
	global_load_dwordx4 v[162:165], v[152:153], off offset:16
	global_load_dwordx4 v[166:169], v[152:153], off
.Lffnup_pf_done:
	s_or_b64 exec, exec, s[100:101]
.Lffnup_pf_skip:
	v_mbcnt_lo_u32_b32 v141, -1, 0
	v_mbcnt_hi_u32_b32 v141, -1, v141
	s_lshl_b32 s12, s38, 7
	v_ashrrev_i32_e32 v140, 1, v141
	s_or_b32 s12, s12, s69
	v_and_b32_e32 v140, -8, v140
	v_add_u32_e32 v140, s12, v140
	s_lshl_b32 s12, s37, 10
	s_and_b32 s12, s12, 0x400
	v_and_or_b32 v147, v141, 15, s68
	s_add_i32 s12, s12, 0
	v_lshl_add_u32 v142, v147, 2, s12
	v_add_u32_e32 v146, 0x20000, v142
	ds_read2_b32 v[142:143], v146 offset1:16
	v_ashrrev_i32_e32 v141, 31, v140
	s_andn2_b64 vcc, exec, s[4:5]
	s_waitcnt lgkmcnt(0)
	v_pk_mul_f32 v[126:127], v[126:127], v[142:143] op_sel_hi:[1,0]
	s_nop 0
	v_mul_f32_e32 v148, 0xbfb8aa3b, v126
	v_mul_f32_e32 v149, 0xbfb8aa3b, v127
	v_exp_f32_e32 v148, v148
	v_exp_f32_e32 v149, v149
	v_pk_mul_f32 v[122:123], v[122:123], v[142:143] op_sel_hi:[1,0]
	v_pk_mul_f32 v[124:125], v[124:125], v[142:143] op_sel_hi:[1,0]
	v_add_f32_e32 v148, 1.0, v148
	v_add_f32_e32 v149, 1.0, v149
	v_rcp_f32_e32 v148, v148
	v_rcp_f32_e32 v149, v149
	v_pk_mul_f32 v[118:119], v[118:119], v[142:143] op_sel_hi:[1,0]
	v_pk_mul_f32 v[114:115], v[114:115], v[142:143] op_sel_hi:[1,0]
	v_pk_mul_f32 v[116:117], v[116:117], v[142:143] op_sel_hi:[1,0]
	v_pk_mul_f32 v[126:127], v[126:127], v[148:149]
	s_nop 0
	v_pk_mul_f32 v[122:123], v[122:123], v[126:127]
	v_pk_mul_f32 v[126:127], v[128:129], v[142:143] op_sel_hi:[1,0]
	s_nop 0
	v_mul_f32_e32 v128, 0xbfb8aa3b, v126
	v_mul_f32_e32 v129, 0xbfb8aa3b, v127
	v_exp_f32_e32 v128, v128
	v_exp_f32_e32 v129, v129
	v_add_f32_e32 v128, 1.0, v128
	v_add_f32_e32 v129, 1.0, v129
	v_rcp_f32_e32 v128, v128
	v_rcp_f32_e32 v129, v129
	s_nop 0
	v_pk_mul_f32 v[126:127], v[126:127], v[128:129]
	s_nop 0
	v_pk_mul_f32 v[124:125], v[124:125], v[126:127]
	v_mul_f32_e32 v126, 0xbfb8aa3b, v118
	v_mul_f32_e32 v127, 0xbfb8aa3b, v119
	v_exp_f32_e32 v126, v126
	v_exp_f32_e32 v127, v127
	v_add_f32_e32 v126, 1.0, v126
	v_add_f32_e32 v127, 1.0, v127
	v_rcp_f32_e32 v126, v126
	v_rcp_f32_e32 v127, v127
	s_nop 0
	v_pk_mul_f32 v[118:119], v[118:119], v[126:127]
	s_nop 0
	v_pk_mul_f32 v[114:115], v[114:115], v[118:119]
	v_pk_mul_f32 v[118:119], v[120:121], v[142:143] op_sel_hi:[1,0]
	s_nop 0
	v_mul_f32_e32 v120, 0xbfb8aa3b, v118
	v_mul_f32_e32 v121, 0xbfb8aa3b, v119
	v_exp_f32_e32 v120, v120
	v_exp_f32_e32 v121, v121
	v_add_f32_e32 v120, 1.0, v120
	v_add_f32_e32 v121, 1.0, v121
	v_rcp_f32_e32 v120, v120
	v_rcp_f32_e32 v121, v121
	s_nop 0
	v_pk_mul_f32 v[118:119], v[118:119], v[120:121]
	s_nop 0
	v_pk_mul_f32 v[116:117], v[116:117], v[118:119]
	v_cvt_pk_bf16_f32 v120, v122, v123
	v_cvt_pk_bf16_f32 v122, v114, v115
	v_lshl_add_u32 v118, s36, 8, v147
	v_mov_b64_e32 v[114:115], s[10:11]
	v_cvt_pk_bf16_f32 v121, v124, v125
	v_cvt_pk_bf16_f32 v123, v116, v117
	v_mad_i64_i32 v[124:125], s[34:35], v118, s55, v[114:115]
	v_lshlrev_b64 v[116:117], 1, v[140:141]
	v_lshl_add_u64 v[124:125], v[124:125], 0, v[116:117]
	global_store_dwordx4 v[124:125], v[120:123], off
	s_mov_b64 s[36:37], -1
	s_nop 0
	v_mov_b32_e32 v120, v143
	v_pk_mul_f32 v[110:111], v[110:111], v[120:121] op_sel_hi:[1,0]
	v_pk_mul_f32 v[106:107], v[106:107], v[120:121] op_sel_hi:[1,0]
	v_mul_f32_e32 v119, 0xbfb8aa3b, v110
	v_exp_f32_e32 v119, v119
	v_pk_mul_f32 v[108:109], v[108:109], v[120:121] op_sel_hi:[1,0]
	v_pk_mul_f32 v[102:103], v[102:103], v[120:121] op_sel_hi:[1,0]
	v_pk_mul_f32 v[98:99], v[98:99], v[120:121] op_sel_hi:[1,0]
	v_add_f32_e32 v119, 1.0, v119
	v_rcp_f32_e32 v122, v119
	v_mul_f32_e32 v119, 0xbfb8aa3b, v111
	v_exp_f32_e32 v119, v119
	v_pk_mul_f32 v[100:101], v[100:101], v[120:121] op_sel_hi:[1,0]
	v_add_f32_e32 v119, 1.0, v119
	v_rcp_f32_e32 v123, v119
	s_nop 0
	v_pk_mul_f32 v[110:111], v[110:111], v[122:123]
	s_nop 0
	v_pk_mul_f32 v[106:107], v[106:107], v[110:111]
	v_pk_mul_f32 v[110:111], v[112:113], v[120:121] op_sel_hi:[1,0]
	s_nop 0
	v_mul_f32_e32 v112, 0xbfb8aa3b, v110
	v_mul_f32_e32 v113, 0xbfb8aa3b, v111
	v_exp_f32_e32 v112, v112
	v_exp_f32_e32 v113, v113
	v_add_f32_e32 v112, 1.0, v112
	v_add_f32_e32 v113, 1.0, v113
	v_rcp_f32_e32 v112, v112
	v_rcp_f32_e32 v113, v113
	s_nop 0
	v_pk_mul_f32 v[110:111], v[110:111], v[112:113]
	s_nop 0
	v_pk_mul_f32 v[108:109], v[108:109], v[110:111]
	v_mul_f32_e32 v110, 0xbfb8aa3b, v102
	v_mul_f32_e32 v111, 0xbfb8aa3b, v103
	v_exp_f32_e32 v110, v110
	v_exp_f32_e32 v111, v111
	v_add_f32_e32 v110, 1.0, v110
	v_add_f32_e32 v111, 1.0, v111
	v_rcp_f32_e32 v110, v110
	v_rcp_f32_e32 v111, v111
	s_nop 0
	v_pk_mul_f32 v[102:103], v[102:103], v[110:111]
	s_nop 0
	v_pk_mul_f32 v[102:103], v[98:99], v[102:103]
	v_pk_mul_f32 v[98:99], v[104:105], v[120:121] op_sel_hi:[1,0]
	s_nop 0
	v_mul_f32_e32 v104, 0xbfb8aa3b, v98
	v_mul_f32_e32 v105, 0xbfb8aa3b, v99
	v_exp_f32_e32 v104, v104
	v_exp_f32_e32 v105, v105
	v_add_f32_e32 v104, 1.0, v104
	v_add_f32_e32 v105, 1.0, v105
	v_rcp_f32_e32 v104, v104
	v_rcp_f32_e32 v105, v105
	s_nop 0
	v_pk_mul_f32 v[98:99], v[98:99], v[104:105]
	s_nop 0
	v_pk_mul_f32 v[104:105], v[100:101], v[98:99]
	v_cvt_pk_bf16_f32 v100, v102, v103
	v_add_u32_e32 v102, 16, v118
	v_mad_i64_i32 v[102:103], s[34:35], v102, s55, v[114:115]
	v_cvt_pk_bf16_f32 v98, v106, v107
	v_cvt_pk_bf16_f32 v99, v108, v109
	v_cvt_pk_bf16_f32 v101, v104, v105
	v_lshl_add_u64 v[102:103], v[102:103], 0, v[116:117]
	global_store_dwordx4 v[102:103], v[98:101], off
	ds_read2_b32 v[98:99], v146 offset0:32 offset1:48
	s_waitcnt lgkmcnt(0)
; __device__ __forceinline__ unsigned cvtpk(float lo, float hi) { f32x2 v = {lo, hi}; bf16x2_t b = __builtin_convertvector(v, bf16x2_t); return __builtin_bit_cast(unsigned, b); }
;     __device__ __forceinline__ void operator()(const f32x4 (&acc)[2][2][4][2], const Unit& u, int ui, int wr, int wc, int fr, int fq) const {
;     ...
;             for (int m = 0; m < 4; ++m) { const int rl = ai * HALF + wr * 64 + m * 16 + fr; const float rs = rsl[(ui & 1) * 256 + rl];
;                 float h[8];
; #pragma unroll
;                 for (int n = 0; n < 2; ++n)
; #pragma unroll
;                     for (int e = 0; e < 4; ++e) { const float g = acc[ai][0][m][n][e] * rs, up = acc[ai][1][m][n][e] * rs;
;                         h[n * 4 + e] = g * __builtin_amdgcn_rcpf(1.f + __builtin_amdgcn_exp2f(-g * LOG2E)) * up; }
;                 u32x4 w; w.x = cvtpk(h[0], h[1]); w.y = cvtpk(h[2], h[3]); w.z = cvtpk(h[4], h[5]); w.w = cvtpk(h[6], h[7]);
;                 *(u32x4*)(H + (size_t)(u.pm * 256 + rl) * DFF + col0) = w; }
	v_pk_mul_f32 v[94:95], v[94:95], v[98:99] op_sel_hi:[1,0]
	s_nop 0
	v_mul_f32_e32 v100, 0xbfb8aa3b, v94
	v_mul_f32_e32 v101, 0xbfb8aa3b, v95
	v_exp_f32_e32 v100, v100
	v_exp_f32_e32 v101, v101
	v_pk_mul_f32 v[90:91], v[90:91], v[98:99] op_sel_hi:[1,0]
	v_pk_mul_f32 v[92:93], v[92:93], v[98:99] op_sel_hi:[1,0]
	v_add_f32_e32 v100, 1.0, v100
	v_add_f32_e32 v101, 1.0, v101
	v_rcp_f32_e32 v100, v100
	v_rcp_f32_e32 v101, v101
	v_pk_mul_f32 v[86:87], v[86:87], v[98:99] op_sel_hi:[1,0]
	v_pk_mul_f32 v[82:83], v[82:83], v[98:99] op_sel_hi:[1,0]
	v_pk_mul_f32 v[84:85], v[84:85], v[98:99] op_sel_hi:[1,0]
	v_pk_mul_f32 v[94:95], v[94:95], v[100:101]
	s_nop 0
	v_pk_mul_f32 v[90:91], v[90:91], v[94:95]
	v_pk_mul_f32 v[94:95], v[96:97], v[98:99] op_sel_hi:[1,0]
	s_nop 0
	v_mul_f32_e32 v96, 0xbfb8aa3b, v94
	v_mul_f32_e32 v97, 0xbfb8aa3b, v95
	v_exp_f32_e32 v96, v96
	v_exp_f32_e32 v97, v97
	v_add_f32_e32 v96, 1.0, v96
	v_add_f32_e32 v97, 1.0, v97
	v_rcp_f32_e32 v96, v96
	v_rcp_f32_e32 v97, v97
	s_nop 0
	v_pk_mul_f32 v[94:95], v[94:95], v[96:97]
	s_nop 0
	v_pk_mul_f32 v[92:93], v[92:93], v[94:95]
	v_mul_f32_e32 v94, 0xbfb8aa3b, v86
	v_mul_f32_e32 v95, 0xbfb8aa3b, v87
	v_exp_f32_e32 v94, v94
	v_exp_f32_e32 v95, v95
	v_add_f32_e32 v94, 1.0, v94
	v_add_f32_e32 v95, 1.0, v95
	v_rcp_f32_e32 v94, v94
	v_rcp_f32_e32 v95, v95
	s_nop 0
	v_pk_mul_f32 v[86:87], v[86:87], v[94:95]
	s_nop 0
	v_pk_mul_f32 v[86:87], v[82:83], v[86:87]
	v_pk_mul_f32 v[82:83], v[88:89], v[98:99] op_sel_hi:[1,0]
	s_nop 0
	v_mul_f32_e32 v88, 0xbfb8aa3b, v82
	v_mul_f32_e32 v89, 0xbfb8aa3b, v83
	v_exp_f32_e32 v88, v88
	v_exp_f32_e32 v89, v89
	v_add_f32_e32 v88, 1.0, v88
	v_add_f32_e32 v89, 1.0, v89
	v_rcp_f32_e32 v88, v88
	v_rcp_f32_e32 v89, v89
	s_nop 0
	v_pk_mul_f32 v[82:83], v[82:83], v[88:89]
	s_nop 0
	v_pk_mul_f32 v[88:89], v[84:85], v[82:83]
	v_cvt_pk_bf16_f32 v84, v86, v87
	v_add_u32_e32 v86, 32, v118
	v_mad_i64_i32 v[86:87], s[34:35], v86, s55, v[114:115]
	v_cvt_pk_bf16_f32 v82, v90, v91
	v_cvt_pk_bf16_f32 v83, v92, v93
	v_cvt_pk_bf16_f32 v85, v88, v89
	v_lshl_add_u64 v[86:87], v[86:87], 0, v[116:117]
	global_store_dwordx4 v[86:87], v[82:85], off
	s_nop 1
	v_mov_b32_e32 v82, v99
	v_pk_mul_f32 v[78:79], v[78:79], v[82:83] op_sel_hi:[1,0]
	s_nop 0
	v_mul_f32_e32 v83, 0xbfb8aa3b, v78
	v_exp_f32_e32 v83, v83
	s_nop 0
	v_add_f32_e32 v83, 1.0, v83
	v_rcp_f32_e32 v84, v83
	v_pk_mul_f32 v[74:75], v[74:75], v[82:83] op_sel_hi:[1,0]
	v_mul_f32_e32 v83, 0xbfb8aa3b, v79
	v_exp_f32_e32 v83, v83
	s_nop 0
	v_add_f32_e32 v83, 1.0, v83
	v_rcp_f32_e32 v85, v83
	v_pk_mul_f32 v[76:77], v[76:77], v[82:83] op_sel_hi:[1,0]
	v_pk_mul_f32 v[70:71], v[70:71], v[82:83] op_sel_hi:[1,0]
	v_pk_mul_f32 v[66:67], v[66:67], v[82:83] op_sel_hi:[1,0]
	v_pk_mul_f32 v[78:79], v[78:79], v[84:85]
	v_pk_mul_f32 v[68:69], v[68:69], v[82:83] op_sel_hi:[1,0]
	v_pk_mul_f32 v[74:75], v[74:75], v[78:79]
	v_pk_mul_f32 v[78:79], v[80:81], v[82:83] op_sel_hi:[1,0]
	s_nop 0
	v_mul_f32_e32 v80, 0xbfb8aa3b, v78
	v_mul_f32_e32 v81, 0xbfb8aa3b, v79
	v_exp_f32_e32 v80, v80
	v_exp_f32_e32 v81, v81
	v_add_f32_e32 v80, 1.0, v80
	v_add_f32_e32 v81, 1.0, v81
	v_rcp_f32_e32 v80, v80
	v_rcp_f32_e32 v81, v81
	s_nop 0
	v_pk_mul_f32 v[78:79], v[78:79], v[80:81]
	s_nop 0
	v_pk_mul_f32 v[76:77], v[76:77], v[78:79]
	v_mul_f32_e32 v78, 0xbfb8aa3b, v70
	v_mul_f32_e32 v79, 0xbfb8aa3b, v71
	v_exp_f32_e32 v78, v78
	v_exp_f32_e32 v79, v79
	v_add_f32_e32 v78, 1.0, v78
	v_add_f32_e32 v79, 1.0, v79
	v_rcp_f32_e32 v78, v78
	v_rcp_f32_e32 v79, v79
	s_nop 0
	v_pk_mul_f32 v[70:71], v[70:71], v[78:79]
	s_nop 0
	v_pk_mul_f32 v[70:71], v[66:67], v[70:71]
	v_pk_mul_f32 v[66:67], v[72:73], v[82:83] op_sel_hi:[1,0]
	s_nop 0
	v_mul_f32_e32 v72, 0xbfb8aa3b, v66
	v_mul_f32_e32 v73, 0xbfb8aa3b, v67
	v_exp_f32_e32 v72, v72
	v_exp_f32_e32 v73, v73
	v_add_f32_e32 v72, 1.0, v72
	v_add_f32_e32 v73, 1.0, v73
	v_rcp_f32_e32 v72, v72
	v_rcp_f32_e32 v73, v73
	s_nop 0
	v_pk_mul_f32 v[66:67], v[66:67], v[72:73]
	s_nop 0
	v_pk_mul_f32 v[72:73], v[68:69], v[66:67]
	v_cvt_pk_bf16_f32 v68, v70, v71
	v_add_u32_e32 v70, 48, v118
	v_mad_i64_i32 v[70:71], s[34:35], v70, s55, v[114:115]
	v_cvt_pk_bf16_f32 v66, v74, v75
	v_cvt_pk_bf16_f32 v67, v76, v77
	v_cvt_pk_bf16_f32 v69, v72, v73
	v_lshl_add_u64 v[70:71], v[70:71], 0, v[116:117]
	global_store_dwordx4 v[70:71], v[66:69], off
	ds_read2_b32 v[66:67], v146 offset0:128 offset1:144
	s_waitcnt lgkmcnt(0)
; __device__ __forceinline__ unsigned cvtpk(float lo, float hi) { f32x2 v = {lo, hi}; bf16x2_t b = __builtin_convertvector(v, bf16x2_t); return __builtin_bit_cast(unsigned, b); }
;     __device__ __forceinline__ void operator()(const f32x4 (&acc)[2][2][4][2], const Unit& u, int ui, int wr, int wc, int fr, int fq) const {
;     ...
;             for (int m = 0; m < 4; ++m) { const int rl = ai * HALF + wr * 64 + m * 16 + fr; const float rs = rsl[(ui & 1) * 256 + rl];
;                 float h[8];
; #pragma unroll
;                 for (int n = 0; n < 2; ++n)
; #pragma unroll
;                     for (int e = 0; e < 4; ++e) { const float g = acc[ai][0][m][n][e] * rs, up = acc[ai][1][m][n][e] * rs;
;                         h[n * 4 + e] = g * __builtin_amdgcn_rcpf(1.f + __builtin_amdgcn_exp2f(-g * LOG2E)) * up; }
;                 u32x4 w; w.x = cvtpk(h[0], h[1]); w.y = cvtpk(h[2], h[3]); w.z = cvtpk(h[4], h[5]); w.w = cvtpk(h[6], h[7]);
;                 *(u32x4*)(H + (size_t)(u.pm * 256 + rl) * DFF + col0) = w; }
	v_pk_mul_f32 v[62:63], v[62:63], v[66:67] op_sel_hi:[1,0]
	s_nop 0
	v_mul_f32_e32 v68, 0xbfb8aa3b, v62
	v_mul_f32_e32 v69, 0xbfb8aa3b, v63
	v_exp_f32_e32 v68, v68
	v_exp_f32_e32 v69, v69
	v_pk_mul_f32 v[58:59], v[58:59], v[66:67] op_sel_hi:[1,0]
	v_pk_mul_f32 v[60:61], v[60:61], v[66:67] op_sel_hi:[1,0]
	v_add_f32_e32 v68, 1.0, v68
	v_add_f32_e32 v69, 1.0, v69
	v_rcp_f32_e32 v68, v68
	v_rcp_f32_e32 v69, v69
	v_pk_mul_f32 v[54:55], v[54:55], v[66:67] op_sel_hi:[1,0]
	v_pk_mul_f32 v[50:51], v[50:51], v[66:67] op_sel_hi:[1,0]
	v_pk_mul_f32 v[52:53], v[52:53], v[66:67] op_sel_hi:[1,0]
	v_pk_mul_f32 v[62:63], v[62:63], v[68:69]
	s_nop 0
	v_pk_mul_f32 v[58:59], v[58:59], v[62:63]
	v_pk_mul_f32 v[62:63], v[64:65], v[66:67] op_sel_hi:[1,0]
	s_nop 0
	v_mul_f32_e32 v64, 0xbfb8aa3b, v62
	v_mul_f32_e32 v65, 0xbfb8aa3b, v63
	v_exp_f32_e32 v64, v64
	v_exp_f32_e32 v65, v65
	v_add_f32_e32 v64, 1.0, v64
	v_add_f32_e32 v65, 1.0, v65
	v_rcp_f32_e32 v64, v64
	v_rcp_f32_e32 v65, v65
	s_nop 0
	v_pk_mul_f32 v[62:63], v[62:63], v[64:65]
	s_nop 0
	v_pk_mul_f32 v[60:61], v[60:61], v[62:63]
	v_mul_f32_e32 v62, 0xbfb8aa3b, v54
	v_mul_f32_e32 v63, 0xbfb8aa3b, v55
	v_exp_f32_e32 v62, v62
	v_exp_f32_e32 v63, v63
	v_add_f32_e32 v62, 1.0, v62
	v_add_f32_e32 v63, 1.0, v63
	v_rcp_f32_e32 v62, v62
	v_rcp_f32_e32 v63, v63
	s_nop 0
	v_pk_mul_f32 v[54:55], v[54:55], v[62:63]
	s_nop 0
	v_pk_mul_f32 v[54:55], v[50:51], v[54:55]
	v_pk_mul_f32 v[50:51], v[56:57], v[66:67] op_sel_hi:[1,0]
	s_nop 0
	v_mul_f32_e32 v56, 0xbfb8aa3b, v50
	v_mul_f32_e32 v57, 0xbfb8aa3b, v51
	v_exp_f32_e32 v56, v56
	v_exp_f32_e32 v57, v57
	v_add_f32_e32 v56, 1.0, v56
	v_add_f32_e32 v57, 1.0, v57
	v_rcp_f32_e32 v56, v56
	v_rcp_f32_e32 v57, v57
	s_nop 0
	v_pk_mul_f32 v[50:51], v[50:51], v[56:57]
	s_nop 0
	v_pk_mul_f32 v[56:57], v[52:53], v[50:51]
	v_cvt_pk_bf16_f32 v52, v54, v55
	v_add_u32_e32 v54, 0x80, v118
	v_mad_i64_i32 v[54:55], s[34:35], v54, s55, v[114:115]
	v_cvt_pk_bf16_f32 v50, v58, v59
	v_cvt_pk_bf16_f32 v51, v60, v61
	v_cvt_pk_bf16_f32 v53, v56, v57
	v_lshl_add_u64 v[54:55], v[54:55], 0, v[116:117]
	global_store_dwordx4 v[54:55], v[50:53], off
	s_nop 1
	v_mov_b32_e32 v50, v67
	v_pk_mul_f32 v[46:47], v[46:47], v[50:51] op_sel_hi:[1,0]
	s_nop 0
	v_mul_f32_e32 v51, 0xbfb8aa3b, v46
	v_exp_f32_e32 v51, v51
	s_nop 0
	v_add_f32_e32 v51, 1.0, v51
	v_rcp_f32_e32 v52, v51
	v_pk_mul_f32 v[42:43], v[42:43], v[50:51] op_sel_hi:[1,0]
	v_mul_f32_e32 v51, 0xbfb8aa3b, v47
	v_exp_f32_e32 v51, v51
	s_nop 0
	v_add_f32_e32 v51, 1.0, v51
	v_rcp_f32_e32 v53, v51
	v_pk_mul_f32 v[44:45], v[44:45], v[50:51] op_sel_hi:[1,0]
	v_pk_mul_f32 v[38:39], v[38:39], v[50:51] op_sel_hi:[1,0]
	v_pk_mul_f32 v[34:35], v[34:35], v[50:51] op_sel_hi:[1,0]
	v_pk_mul_f32 v[46:47], v[46:47], v[52:53]
	v_pk_mul_f32 v[36:37], v[36:37], v[50:51] op_sel_hi:[1,0]
	v_pk_mul_f32 v[42:43], v[42:43], v[46:47]
	v_pk_mul_f32 v[46:47], v[48:49], v[50:51] op_sel_hi:[1,0]
	s_nop 0
	v_mul_f32_e32 v48, 0xbfb8aa3b, v46
	v_mul_f32_e32 v49, 0xbfb8aa3b, v47
	v_exp_f32_e32 v48, v48
	v_exp_f32_e32 v49, v49
	v_add_f32_e32 v48, 1.0, v48
	v_add_f32_e32 v49, 1.0, v49
	v_rcp_f32_e32 v48, v48
	v_rcp_f32_e32 v49, v49
	s_nop 0
	v_pk_mul_f32 v[46:47], v[46:47], v[48:49]
	s_nop 0
	v_pk_mul_f32 v[44:45], v[44:45], v[46:47]
	v_mul_f32_e32 v46, 0xbfb8aa3b, v38
	v_mul_f32_e32 v47, 0xbfb8aa3b, v39
	v_exp_f32_e32 v46, v46
	v_exp_f32_e32 v47, v47
	v_add_f32_e32 v46, 1.0, v46
	v_add_f32_e32 v47, 1.0, v47
	v_rcp_f32_e32 v46, v46
	v_rcp_f32_e32 v47, v47
	s_nop 0
	v_pk_mul_f32 v[38:39], v[38:39], v[46:47]
	s_nop 0
	v_pk_mul_f32 v[38:39], v[34:35], v[38:39]
	v_pk_mul_f32 v[34:35], v[40:41], v[50:51] op_sel_hi:[1,0]
	s_nop 0
	v_mul_f32_e32 v40, 0xbfb8aa3b, v34
	v_mul_f32_e32 v41, 0xbfb8aa3b, v35
	v_exp_f32_e32 v40, v40
	v_exp_f32_e32 v41, v41
	v_add_f32_e32 v40, 1.0, v40
	v_add_f32_e32 v41, 1.0, v41
	v_rcp_f32_e32 v40, v40
	v_rcp_f32_e32 v41, v41
	s_nop 0
	v_pk_mul_f32 v[34:35], v[34:35], v[40:41]
	s_nop 0
	v_pk_mul_f32 v[40:41], v[36:37], v[34:35]
	v_cvt_pk_bf16_f32 v36, v38, v39
	v_add_u32_e32 v38, 0x90, v118
	v_mad_i64_i32 v[38:39], s[34:35], v38, s55, v[114:115]
	v_cvt_pk_bf16_f32 v34, v42, v43
	v_cvt_pk_bf16_f32 v35, v44, v45
	v_cvt_pk_bf16_f32 v37, v40, v41
	v_lshl_add_u64 v[38:39], v[38:39], 0, v[116:117]
	global_store_dwordx4 v[38:39], v[34:37], off
	ds_read2_b32 v[34:35], v146 offset0:160 offset1:176
	s_waitcnt lgkmcnt(0)
; __device__ __forceinline__ unsigned cvtpk(float lo, float hi) { f32x2 v = {lo, hi}; bf16x2_t b = __builtin_convertvector(v, bf16x2_t); return __builtin_bit_cast(unsigned, b); }
; __device__ __forceinline__ void rs_prep(const float* ssq, int tok0, LAS float* rsl, int ui, int wv) {
;     ...
;     if (tid < 256) { const f32x4* s = (const f32x4*)(ssq + (size_t)(tok0 + tid) * 16); const f32x4 a = s[0], b = s[1], c = s[2], d = s[3];
;         const float t = ((a.x + a.y) + (a.z + a.w)) + ((b.x + b.y) + (b.z + b.w)) + ((c.x + c.y) + (c.z + c.w)) + ((d.x + d.y) + (d.z + d.w));
;         rsl[(ui & 1) * 256 + tid] = rsqrtf(t * (1.f / 1024.f) + EPS); }
;     __device__ __forceinline__ void operator()(const f32x4 (&acc)[2][2][4][2], const Unit& u, int ui, int wr, int wc, int fr, int fq) const {
;     ...
;             for (int m = 0; m < 4; ++m) { const int rl = ai * HALF + wr * 64 + m * 16 + fr; const float rs = rsl[(ui & 1) * 256 + rl];
;                 float h[8];
; #pragma unroll
;                 for (int n = 0; n < 2; ++n)
; #pragma unroll
;                     for (int e = 0; e < 4; ++e) { const float g = acc[ai][0][m][n][e] * rs, up = acc[ai][1][m][n][e] * rs;
;                         h[n * 4 + e] = g * __builtin_amdgcn_rcpf(1.f + __builtin_amdgcn_exp2f(-g * LOG2E)) * up; }
;                 u32x4 w; w.x = cvtpk(h[0], h[1]); w.y = cvtpk(h[2], h[3]); w.z = cvtpk(h[4], h[5]); w.w = cvtpk(h[6], h[7]);
;                 *(u32x4*)(H + (size_t)(u.pm * 256 + rl) * DFF + col0) = w; }
	v_pk_mul_f32 v[30:31], v[30:31], v[34:35] op_sel_hi:[1,0]
	s_nop 0
	v_mul_f32_e32 v36, 0xbfb8aa3b, v30
	v_mul_f32_e32 v37, 0xbfb8aa3b, v31
	v_exp_f32_e32 v36, v36
	v_exp_f32_e32 v37, v37
	v_pk_mul_f32 v[26:27], v[26:27], v[34:35] op_sel_hi:[1,0]
	v_pk_mul_f32 v[28:29], v[28:29], v[34:35] op_sel_hi:[1,0]
	v_add_f32_e32 v36, 1.0, v36
	v_add_f32_e32 v37, 1.0, v37
	v_rcp_f32_e32 v36, v36
	v_rcp_f32_e32 v37, v37
	v_pk_mul_f32 v[22:23], v[22:23], v[34:35] op_sel_hi:[1,0]
	v_pk_mul_f32 v[18:19], v[18:19], v[34:35] op_sel_hi:[1,0]
	v_pk_mul_f32 v[20:21], v[20:21], v[34:35] op_sel_hi:[1,0]
	v_pk_mul_f32 v[30:31], v[30:31], v[36:37]
	s_nop 0
	v_pk_mul_f32 v[26:27], v[26:27], v[30:31]
	v_pk_mul_f32 v[30:31], v[32:33], v[34:35] op_sel_hi:[1,0]
	s_nop 0
	v_mul_f32_e32 v32, 0xbfb8aa3b, v30
	v_mul_f32_e32 v33, 0xbfb8aa3b, v31
	v_exp_f32_e32 v32, v32
	v_exp_f32_e32 v33, v33
	v_add_f32_e32 v32, 1.0, v32
	v_add_f32_e32 v33, 1.0, v33
	v_rcp_f32_e32 v32, v32
	v_rcp_f32_e32 v33, v33
	s_nop 0
	v_pk_mul_f32 v[30:31], v[30:31], v[32:33]
	s_nop 0
	v_pk_mul_f32 v[28:29], v[28:29], v[30:31]
	v_mul_f32_e32 v30, 0xbfb8aa3b, v22
	v_mul_f32_e32 v31, 0xbfb8aa3b, v23
	v_exp_f32_e32 v30, v30
	v_exp_f32_e32 v31, v31
	v_add_f32_e32 v30, 1.0, v30
	v_add_f32_e32 v31, 1.0, v31
	v_rcp_f32_e32 v30, v30
	v_rcp_f32_e32 v31, v31
	s_nop 0
	v_pk_mul_f32 v[22:23], v[22:23], v[30:31]
	s_nop 0
	v_pk_mul_f32 v[22:23], v[18:19], v[22:23]
	v_pk_mul_f32 v[18:19], v[24:25], v[34:35] op_sel_hi:[1,0]
	s_nop 0
	v_mul_f32_e32 v24, 0xbfb8aa3b, v18
	v_mul_f32_e32 v25, 0xbfb8aa3b, v19
	v_exp_f32_e32 v24, v24
	v_exp_f32_e32 v25, v25
	v_add_f32_e32 v24, 1.0, v24
	v_add_f32_e32 v25, 1.0, v25
	v_rcp_f32_e32 v24, v24
	v_rcp_f32_e32 v25, v25
	s_nop 0
	v_pk_mul_f32 v[18:19], v[18:19], v[24:25]
	s_nop 0
	v_pk_mul_f32 v[24:25], v[20:21], v[18:19]
	v_cvt_pk_bf16_f32 v20, v22, v23
	v_add_u32_e32 v22, 0xa0, v118
	v_mad_i64_i32 v[22:23], s[34:35], v22, s55, v[114:115]
	v_cvt_pk_bf16_f32 v18, v26, v27
	v_cvt_pk_bf16_f32 v19, v28, v29
	v_cvt_pk_bf16_f32 v21, v24, v25
	v_lshl_add_u64 v[22:23], v[22:23], 0, v[116:117]
	global_store_dwordx4 v[22:23], v[18:21], off
	s_nop 1
	v_mov_b32_e32 v18, v35
	v_pk_mul_f32 v[14:15], v[14:15], v[18:19] op_sel_hi:[1,0]
	s_nop 0
	v_mul_f32_e32 v19, 0xbfb8aa3b, v14
	v_exp_f32_e32 v19, v19
	s_nop 0
	v_add_f32_e32 v19, 1.0, v19
	v_rcp_f32_e32 v20, v19
	v_pk_mul_f32 v[10:11], v[10:11], v[18:19] op_sel_hi:[1,0]
	v_mul_f32_e32 v19, 0xbfb8aa3b, v15
	v_exp_f32_e32 v19, v19
	s_nop 0
	v_add_f32_e32 v19, 1.0, v19
	v_rcp_f32_e32 v21, v19
	v_pk_mul_f32 v[12:13], v[12:13], v[18:19] op_sel_hi:[1,0]
	v_pk_mul_f32 v[6:7], v[6:7], v[18:19] op_sel_hi:[1,0]
	v_pk_mul_f32 v[2:3], v[2:3], v[18:19] op_sel_hi:[1,0]
	v_pk_mul_f32 v[14:15], v[14:15], v[20:21]
	v_pk_mul_f32 v[4:5], v[4:5], v[18:19] op_sel_hi:[1,0]
	v_pk_mul_f32 v[10:11], v[10:11], v[14:15]
	v_pk_mul_f32 v[14:15], v[16:17], v[18:19] op_sel_hi:[1,0]
	s_nop 0
	v_mul_f32_e32 v16, 0xbfb8aa3b, v14
	v_mul_f32_e32 v17, 0xbfb8aa3b, v15
	v_exp_f32_e32 v16, v16
	v_exp_f32_e32 v17, v17
	v_add_f32_e32 v16, 1.0, v16
	v_add_f32_e32 v17, 1.0, v17
	v_rcp_f32_e32 v16, v16
	v_rcp_f32_e32 v17, v17
	s_nop 0
	v_pk_mul_f32 v[14:15], v[14:15], v[16:17]
	s_nop 0
	v_pk_mul_f32 v[12:13], v[12:13], v[14:15]
	v_mul_f32_e32 v14, 0xbfb8aa3b, v6
	v_mul_f32_e32 v15, 0xbfb8aa3b, v7
	v_exp_f32_e32 v14, v14
	v_exp_f32_e32 v15, v15
	v_add_f32_e32 v14, 1.0, v14
	v_add_f32_e32 v15, 1.0, v15
	v_rcp_f32_e32 v14, v14
	v_rcp_f32_e32 v15, v15
	s_nop 0
	v_pk_mul_f32 v[6:7], v[6:7], v[14:15]
	s_nop 0
	v_pk_mul_f32 v[6:7], v[2:3], v[6:7]
	v_pk_mul_f32 v[2:3], v[8:9], v[18:19] op_sel_hi:[1,0]
	s_nop 0
	v_mul_f32_e32 v8, 0xbfb8aa3b, v2
	v_mul_f32_e32 v9, 0xbfb8aa3b, v3
	v_exp_f32_e32 v8, v8
	v_exp_f32_e32 v9, v9
	v_add_f32_e32 v8, 1.0, v8
	v_add_f32_e32 v9, 1.0, v9
	v_rcp_f32_e32 v8, v8
	v_rcp_f32_e32 v9, v9
	s_nop 0
	v_pk_mul_f32 v[2:3], v[2:3], v[8:9]
	s_nop 0
	v_pk_mul_f32 v[8:9], v[4:5], v[2:3]
	v_cvt_pk_bf16_f32 v4, v6, v7
	v_add_u32_e32 v6, 0xb0, v118
	v_mad_i64_i32 v[6:7], s[34:35], v6, s55, v[114:115]
	v_cvt_pk_bf16_f32 v2, v10, v11
	v_cvt_pk_bf16_f32 v3, v12, v13
	v_cvt_pk_bf16_f32 v5, v8, v9
	v_lshl_add_u64 v[6:7], v[6:7], 0, v[116:117]
	global_store_dwordx4 v[6:7], v[2:5], off
	s_cbranch_vccnz .LBB0_1159
	s_nop 0
	v_mbcnt_lo_u32_b32 v2, -1, 0
	v_mbcnt_hi_u32_b32 v2, -1, v2
	s_nop 0
	v_add_u32_e32 v2, s16, v2
	v_cmp_gt_i32_e32 vcc, s88, v2
	s_and_saveexec_b64 s[4:5], vcc
	s_cbranch_execz .LBB0_1169
	s_lshl_b32 s12, s82, 10
	s_and_b32 s12, s12, 0x400
	s_add_i32 s12, s12, 0
	v_lshl_add_u32 v2, v2, 2, s12
	v_add_u32_e32 v2, 0x20000, v2
	s_waitcnt vmcnt(8)
	v_mov_b64_e32 v[4:5], v[154:155]
	v_mov_b64_e32 v[6:7], v[156:157]
	v_mov_b64_e32 v[8:9], v[158:159]
	v_mov_b64_e32 v[10:11], v[160:161]
	v_mov_b64_e32 v[12:13], v[162:163]
	v_mov_b64_e32 v[14:15], v[164:165]
	v_mov_b64_e32 v[16:17], v[166:167]
	v_mov_b64_e32 v[18:19], v[168:169]
	v_add_f32_e32 v8, v8, v9
	v_add_f32_e32 v10, v10, v11
	v_mov_b32_e32 v20, v17
	v_mov_b32_e32 v21, v18
	v_mov_b32_e32 v17, v19
	v_mov_b32_e32 v18, v13
	v_mov_b32_e32 v19, v14
	v_mov_b32_e32 v13, v15
	v_pk_add_f32 v[16:17], v[20:21], v[16:17]
	v_pk_add_f32 v[12:13], v[18:19], v[12:13]
	v_pk_add_f32 v[16:17], v[16:17], v[16:17] op_sel:[0,1] op_sel_hi:[1,0]
	v_pk_add_f32 v[12:13], v[12:13], v[12:13] op_sel:[0,1] op_sel_hi:[1,0]
	v_mov_b32_e32 v17, v4
	v_mov_b32_e32 v13, v5
	v_mov_b32_e32 v9, v6
	v_mov_b32_e32 v11, v7
	v_pk_add_f32 v[4:5], v[16:17], v[12:13]
	v_pk_add_f32 v[6:7], v[8:9], v[10:11]
	s_nop 0
	v_pk_add_f32 v[4:5], v[4:5], v[6:7]
	s_nop 0
	v_add_f32_e32 v3, v4, v5
	v_fmamk_f32 v3, v3, 0x3a800000, v254
	v_cmp_gt_f32_e32 vcc, s56, v3
	v_mul_f32_e32 v4, 0x4b800000, v3
	s_nop 0
	v_cndmask_b32_e32 v3, v3, v4, vcc
	v_rsq_f32_e32 v3, v3
	s_nop 0
	v_mul_f32_e32 v4, 0x45800000, v3
	v_cndmask_b32_e32 v3, v3, v4, vcc
	ds_write_b32 v2, v3
